# ret_out epilogue: all 24 gate/norm-parameter loads issued at epilogue start into free VGPRs, per-element vmcnt waits (which also waited on store acks) removed
# speedup vs baseline: 1.0074x; 1.0074x over previous
.LBB0_1085:
	ds_read_b128 v[106:109], v129
	ds_read_b128 v[130:133], v129 offset:64
	s_add_i32 s2, s2, 32
	s_waitcnt vmcnt(1) lgkmcnt(1)
	v_mfma_f32_16x16x32_bf16 v[106:109], v[106:109], v[102:105], 0
	ds_read_b128 v[134:137], v129 offset:2368
	s_waitcnt vmcnt(0) lgkmcnt(1)
	v_mfma_f32_16x16x32_bf16 v[106:109], v[130:133], v[70:73], v[106:109]
	ds_read_b128 v[130:133], v129 offset:2304
	v_add_u32_e32 v129, 0x1200, v129
	s_waitcnt lgkmcnt(0)
	v_mfma_f32_16x16x32_bf16 v[130:133], v[130:133], v[102:105], 0
	s_nop 3
	v_mul_f32_e32 v106, 0x3e000000, v106
	v_mul_f32_e32 v107, 0x3e000000, v107
	v_mul_f32_e64 v108, v108, s18
	v_mul_f32_e64 v109, v109, s18
	v_mfma_f32_16x16x32_bf16 v[130:133], v[134:137], v[70:73], v[130:133]
	v_add_u32_e32 v135, v122, v112
	v_cvt_f32_u32_e32 v137, v135
	v_add_u32_e32 v136, -16, v135
	v_cmp_lt_i32_e32 vcc, -1, v135
	v_add_u32_e32 v134, s2, v114
	v_mul_f32_e32 v137, v115, v137
	v_mul_f32_e32 v137, 0x3fb8aa3b, v137
	v_exp_f32_e32 v137, v137
	v_subrev_u32_e32 v112, 32, v112
	v_mul_f32_e32 v106, v106, v137
	v_cndmask_b32_e32 v137, 0, v106, vcc
	v_mul_f32_e32 v106, 0x3e000000, v130
	v_cvt_f32_u32_e32 v130, v136
	v_cmp_lt_i32_e32 vcc, 15, v135
	v_mul_f32_e32 v130, v115, v130
	v_mul_f32_e32 v130, 0x3fb8aa3b, v130
	v_exp_f32_e32 v130, v130
	s_nop 0
	v_mul_f32_e32 v106, v130, v106
	v_cndmask_b32_e32 v136, 0, v106, vcc
	v_add_u32_e32 v106, -1, v135
	v_subrev_u32_e32 v130, 17, v135
	v_cvt_f32_u32_e32 v135, v106
	v_cmp_lt_i32_e32 vcc, -1, v106
	v_mul_f32_e32 v135, v115, v135
	v_mul_f32_e32 v135, 0x3fb8aa3b, v135
	v_exp_f32_e32 v135, v135
	s_nop 0
	v_mul_f32_e32 v107, v107, v135
	v_cndmask_b32_e32 v135, 0, v107, vcc
	v_cvt_f32_u32_e32 v107, v130
	v_cmp_lt_i32_e32 vcc, 15, v106
	v_mul_f32_e32 v106, 0x3e000000, v131
	v_mul_f32_e32 v107, v115, v107
	v_mul_f32_e32 v107, 0x3fb8aa3b, v107
	v_exp_f32_e32 v107, v107
	s_nop 0
	v_mul_f32_e32 v106, v107, v106
	v_or_b32_e32 v107, 2, v134
	v_cndmask_b32_e32 v138, 0, v106, vcc
	v_or_b32_e32 v106, 3, v134
	v_sub_u32_e32 v134, v110, v107
	v_add_u32_e32 v107, -16, v134
	v_cvt_f32_u32_e32 v107, v107
	v_sub_u32_e32 v131, v111, v106
	v_cvt_f32_u32_e32 v106, v134
	v_add_u32_e32 v139, -16, v131
	v_mul_f32_e32 v107, v115, v107
	v_mul_f32_e32 v107, 0x3fb8aa3b, v107
	v_exp_f32_e32 v130, v107
	v_cvt_f32_u32_e32 v107, v131
	v_cmp_lt_i32_e32 vcc, -1, v131
	v_cmp_lt_i32_e64 s[8:9], 15, v131
	v_cvt_f32_u32_e32 v131, v139
	v_mul_f32_e32 v106, v115, v106
	v_mul_f32_e32 v107, v115, v107
	v_mul_f32_e32 v106, 0x3fb8aa3b, v106
	v_mul_f32_e32 v107, 0x3fb8aa3b, v107
	v_mul_f32_e32 v131, v115, v131
	v_exp_f32_e32 v106, v106
	v_exp_f32_e32 v107, v107
	v_mul_f32_e32 v131, 0x3fb8aa3b, v131
	v_exp_f32_e32 v131, v131
	v_cmp_lt_i32_e64 s[10:11], 15, v134
	v_mul_f32_e64 v108, v108, v106
	v_mul_f32_e64 v109, v109, v107
	v_mul_f32_e64 v106, v132, s18
	v_mul_f32_e64 v107, v133, s18
	v_cmp_lt_i32_e64 s[0:1], -1, v134
	v_mul_f32_e64 v130, v130, v106
	v_mul_f32_e64 v131, v131, v107
	v_cvt_pk_bf16_f32 v107, v108, v109
	v_cvt_pk_bf16_f32 v109, v130, v131
	v_cndmask_b32_e64 v130, 0, v109, s[10:11]
	v_lshrrev_b32_e32 v109, 16, v109
	v_cndmask_b32_e64 v109, 0, v109, s[8:9]
	v_perm_b32 v109, v109, v130, s19
	ds_read2_b64 v[130:133], v113 offset1:4
	v_cndmask_b32_e64 v108, 0, v107, s[0:1]
	v_lshrrev_b32_e32 v107, 16, v107
	v_cndmask_b32_e32 v107, 0, v107, vcc
	v_cvt_pk_bf16_f32 v106, v137, v135
	v_perm_b32 v107, v107, v108, s19
	v_cvt_pk_bf16_f32 v108, v136, v138
	v_cmp_eq_u32_e32 vcc, s2, v122
	s_or_b64 s[16:17], vcc, s[16:17]
	s_waitcnt lgkmcnt(0)
	v_mfma_f32_16x16x32_bf16 v[98:101], v[130:133], v[106:109], v[98:101]
	v_add_u32_e32 v130, 0x1000, v113
	ds_read2_b64 v[130:133], v130 offset0:32 offset1:36
	s_waitcnt lgkmcnt(0)
	v_mfma_f32_16x16x32_bf16 v[82:85], v[130:133], v[106:109], v[82:85]
	v_add_u32_e32 v130, 0x2000, v113
	ds_read2_b64 v[130:133], v130 offset0:64 offset1:68
	s_waitcnt lgkmcnt(0)
	v_mfma_f32_16x16x32_bf16 v[74:77], v[130:133], v[106:109], v[74:77]
	v_add_u32_e32 v130, 0x3000, v113
	ds_read2_b64 v[130:133], v130 offset0:96 offset1:100
	s_waitcnt lgkmcnt(0)
	v_mfma_f32_16x16x32_bf16 v[66:69], v[130:133], v[106:109], v[66:69]
	v_add_u32_e32 v130, 0x4000, v113
	ds_read2_b64 v[130:133], v130 offset0:128 offset1:132
	s_waitcnt lgkmcnt(0)
	v_mfma_f32_16x16x32_bf16 v[90:93], v[130:133], v[106:109], v[90:93]
	v_add_u32_e32 v130, 0x5000, v113
	ds_read2_b64 v[130:133], v130 offset0:160 offset1:164
	s_waitcnt lgkmcnt(0)
	v_mfma_f32_16x16x32_bf16 v[94:97], v[130:133], v[106:109], v[94:97]
	v_add_u32_e32 v130, 0x6000, v113
	ds_read2_b64 v[130:133], v130 offset0:192 offset1:196
	s_waitcnt lgkmcnt(0)
	v_mfma_f32_16x16x32_bf16 v[86:89], v[130:133], v[106:109], v[86:89]
	v_add_u32_e32 v130, 0x7000, v113
	ds_read2_b64 v[130:133], v130 offset0:224 offset1:228
	v_add_u32_e32 v113, 64, v113
	s_waitcnt lgkmcnt(0)
	v_mfma_f32_16x16x32_bf16 v[78:81], v[130:133], v[106:109], v[78:81]
	s_andn2_b64 exec, exec, s[16:17]
	s_cbranch_execnz .LBB0_1085
	s_or_b64 exec, exec, s[16:17]
	v_add_u32_e32 v106, 1, v110
	v_cvt_f32_u32_e32 v107, v106
	v_lshlrev_b32_e32 v106, 16, v102
	s_mov_b32 s13, s89
	s_brev_b32 s0, 60
	v_mul_f32_e32 v107, v115, v107
	v_mul_f32_e32 v107, 0x3fb8aa3b, v107
	v_exp_f32_e32 v108, v107
	v_and_b32_e32 v107, 0xffff0000, v102
	v_lshlrev_b32_e32 v102, 16, v103
	v_and_b32_e32 v103, 0xffff0000, v103
	v_mul_f32_e64 v102, v108, v102
	v_mul_f32_e64 v103, v108, v103
	v_cvt_pk_bf16_f32 v131, v102, v103
	v_lshlrev_b32_e32 v102, 16, v104
	v_and_b32_e32 v103, 0xffff0000, v104
	v_mul_f32_e64 v102, v108, v102
	v_mul_f32_e64 v103, v108, v103
	v_cvt_pk_bf16_f32 v132, v102, v103
	v_lshlrev_b32_e32 v102, 16, v105
	v_and_b32_e32 v103, 0xffff0000, v105
	v_mul_f32_e64 v102, v108, v102
	v_mul_f32_e64 v103, v108, v103
	v_cvt_pk_bf16_f32 v133, v102, v103
	v_lshlrev_b32_e32 v102, 16, v70
	v_and_b32_e32 v103, 0xffff0000, v70
	v_lshlrev_b32_e32 v70, 16, v71
	v_and_b32_e32 v71, 0xffff0000, v71
	v_mul_f32_e64 v106, v108, v106
	v_mul_f32_e64 v107, v108, v107
	v_mul_f32_e64 v70, v108, v70
	v_mul_f32_e64 v71, v108, v71
	v_cvt_pk_bf16_f32 v130, v106, v107
	v_cvt_pk_bf16_f32 v135, v70, v71
	v_lshlrev_b32_e32 v70, 16, v72
	v_and_b32_e32 v71, 0xffff0000, v72
	v_mul_f32_e64 v70, v108, v70
	v_mul_f32_e64 v71, v108, v71
	v_mfma_f32_16x16x32_bf16 v[98:101], v[2:5], v[130:133], v[98:101]
	v_cvt_pk_bf16_f32 v136, v70, v71
	v_lshlrev_b32_e32 v70, 16, v73
	v_and_b32_e32 v71, 0xffff0000, v73
	v_mfma_f32_16x16x32_bf16 v[66:69], v[26:29], v[130:133], v[66:69]
	v_mul_f32_e64 v102, v108, v102
	v_mul_f32_e64 v103, v108, v103
	v_mul_f32_e64 v70, v108, v70
	v_mul_f32_e64 v71, v108, v71
	v_cvt_pk_bf16_f32 v134, v102, v103
	v_cvt_pk_bf16_f32 v137, v70, v71
	v_mfma_f32_16x16x32_bf16 v[70:73], v[10:13], v[130:133], v[82:85]
	s_mov_b32 s2, 16
	v_mfma_f32_16x16x32_bf16 v[110:113], v[6:9], v[134:137], v[98:101]
	v_mfma_f32_16x16x32_bf16 v[98:101], v[30:33], v[134:137], v[66:69]
	v_mfma_f32_16x16x32_bf16 v[66:69], v[34:37], v[130:133], v[90:93]
	s_nop 5
	v_mul_f32_e32 v129, v111, v111
	v_fmac_f32_e32 v129, v110, v110
	v_fmac_f32_e32 v129, v112, v112
	v_mfma_f32_16x16x32_bf16 v[82:85], v[38:41], v[134:137], v[66:69]
	v_fmac_f32_e32 v129, v113, v113
	v_mfma_f32_16x16x32_bf16 v[66:69], v[42:45], v[130:133], v[94:97]
	v_mfma_f32_16x16x32_bf16 v[106:109], v[14:17], v[134:137], v[70:73]
	v_mfma_f32_16x16x32_bf16 v[70:73], v[18:21], v[130:133], v[74:77]
	v_mfma_f32_16x16x32_bf16 v[74:77], v[46:49], v[134:137], v[66:69]
	s_nop 5
	v_fmac_f32_e32 v129, v106, v106
	v_fmac_f32_e32 v129, v107, v107
	v_fmac_f32_e32 v129, v108, v108
	v_mfma_f32_16x16x32_bf16 v[66:69], v[50:53], v[130:133], v[86:89]
	v_fmac_f32_e32 v129, v109, v109
	v_mfma_f32_16x16x32_bf16 v[102:105], v[22:25], v[134:137], v[70:73]
	s_nop 2
	v_add_f32_e32 v70, 0, v110
	v_add_f32_e32 v86, v111, v70
	v_mfma_f32_16x16x32_bf16 v[70:73], v[54:57], v[134:137], v[66:69]
	s_nop 1
	v_fmac_f32_e32 v129, v102, v102
	v_fmac_f32_e32 v129, v103, v103
	v_fmac_f32_e32 v129, v104, v104
	v_add_f32_e32 v66, v112, v86
	v_add_f32_e32 v86, v113, v66
	v_mfma_f32_16x16x32_bf16 v[66:69], v[58:61], v[130:133], v[78:81]
	v_fmac_f32_e32 v129, v105, v105
	v_fmac_f32_e32 v129, v98, v98
	v_fmac_f32_e32 v129, v99, v99
	v_add_f32_e32 v78, v86, v106
	v_add_f32_e32 v78, v107, v78
	v_add_f32_e32 v78, v108, v78
	v_add_f32_e32 v78, v109, v78
	v_add_f32_e32 v78, v78, v102
	v_add_f32_e32 v78, v103, v78
	v_add_f32_e32 v78, v104, v78
	v_add_f32_e32 v78, v105, v78
	v_add_f32_e32 v78, v78, v98
	v_add_f32_e32 v90, v99, v78
	v_lshl_add_u64 v[78:79], v[120:121], 0, s[12:13]
	v_lshlrev_b32_e32 v80, 1, v114
	v_mov_b32_e32 v81, v1
	v_lshl_add_u64 v[86:87], v[78:79], 0, v[80:81]
	v_add_co_u32_e32 v96, vcc, s68, v86
	v_add_f32_e32 v78, v100, v90
	s_nop 0
	v_addc_co_u32_e32 v97, vcc, 0, v87, vcc
	global_load_dwordx2 v[140:141], v[96:97], off
	global_load_dwordx2 v[142:143], v[96:97], off offset:32
	global_load_dwordx2 v[144:145], v[96:97], off offset:64
	global_load_dwordx2 v[146:147], v[96:97], off offset:96
	global_load_dwordx2 v[148:149], v[96:97], off offset:128
	global_load_dwordx2 v[150:151], v[96:97], off offset:160
	global_load_dwordx2 v[152:153], v[96:97], off offset:192
	global_load_dwordx2 v[154:155], v[96:97], off offset:224
	global_load_dwordx4 v[156:159], v[116:117], off
	global_load_dwordx4 v[160:163], v[116:117], off offset:64
	global_load_dwordx4 v[164:167], v[116:117], off offset:128
	global_load_dwordx4 v[168:171], v[116:117], off offset:192
	global_load_dwordx4 v[172:175], v[116:117], off offset:256
	global_load_dwordx4 v[176:179], v[116:117], off offset:320
	global_load_dwordx4 v[180:183], v[116:117], off offset:384
	global_load_dwordx4 v[184:187], v[116:117], off offset:448
	global_load_dwordx4 v[196:199], v[118:119], off
	global_load_dwordx4 v[200:203], v[118:119], off offset:64
	global_load_dwordx4 v[204:207], v[118:119], off offset:128
	global_load_dwordx4 v[208:211], v[118:119], off offset:192
	global_load_dwordx4 v[212:215], v[118:119], off offset:256
	global_load_dwordx4 v[216:219], v[118:119], off offset:320
	global_load_dwordx4 v[220:223], v[118:119], off offset:384
	global_load_dwordx4 v[224:227], v[118:119], off offset:448
	v_add_f32_e32 v78, v101, v78
	v_add_f32_e32 v78, v78, v82
	v_add_f32_e32 v78, v83, v78
	v_add_f32_e32 v78, v84, v78
	v_add_f32_e32 v90, v85, v78
	v_fmac_f32_e32 v129, v100, v100
	v_fmac_f32_e32 v129, v101, v101
	v_fmac_f32_e32 v129, v82, v82
	v_fmac_f32_e32 v129, v83, v83
	v_add_f32_e32 v120, v90, v74
	v_pk_mov_b32 v[90:91], v[84:85], v[74:75] op_sel:[1,0]
	v_fmac_f32_e32 v129, v84, v84
	v_mul_f32_e64 v90, v90, v90
	v_mul_f32_e64 v91, v91, v91
	v_mfma_f32_16x16x32_bf16 v[66:69], v[62:65], v[134:137], v[66:69]
	v_add_f32_e32 v90, v90, v129
	v_add_f32_e32 v129, v90, v91
	v_add_f32_e32 v90, v75, v120
	v_add_f32_e32 v130, v76, v90
	v_mul_f32_e64 v90, v76, v76
	v_mul_f32_e64 v91, v77, v77
	v_mul_f32_e64 v120, v74, v74
	v_mul_f32_e64 v121, v75, v75
	s_nop 0
	v_add_f32_e32 v91, v121, v129
	v_add_f32_e32 v120, v90, v91
	v_add_f32_e32 v90, v77, v130
	v_add_f32_e32 v121, v90, v70
	v_pk_mov_b32 v[90:91], v[76:77], v[70:71] op_sel:[1,0]
	s_nop 0
	v_mul_f32_e64 v90, v90, v90
	v_mul_f32_e64 v91, v91, v91
	s_nop 0
	v_add_f32_e32 v90, v90, v120
	v_add_f32_e32 v129, v90, v91
	v_add_f32_e32 v90, v71, v121
	v_add_f32_e32 v130, v72, v90
	v_mul_f32_e64 v90, v72, v72
	v_mul_f32_e64 v91, v73, v73
	v_mul_f32_e64 v120, v70, v70
	v_mul_f32_e64 v121, v71, v71
	s_nop 0
	v_add_f32_e32 v91, v121, v129
	v_add_f32_e32 v120, v90, v91
	v_add_f32_e32 v90, v73, v130
	v_add_f32_e32 v121, v90, v66
	v_pk_mov_b32 v[90:91], v[72:73], v[66:67] op_sel:[1,0]
	v_mul_f32_e64 v130, v66, v66
	v_mul_f32_e64 v131, v67, v67
	v_mul_f32_e64 v90, v90, v90
	v_mul_f32_e64 v91, v91, v91
	s_waitcnt vmcnt(0)
	v_mov_b32_e32 v88, v140
	v_mov_b32_e32 v89, v141
	v_mov_b32_e32 v78, v156
	v_mov_b32_e32 v79, v157
	v_mov_b32_e32 v80, v158
	v_mov_b32_e32 v81, v159
	v_mov_b32_e32 v92, v196
	v_mov_b32_e32 v93, v197
	v_mov_b32_e32 v94, v198
	v_mov_b32_e32 v95, v199
	v_lshlrev_b32_e32 v130, 16, v88
	v_add_f32_e32 v90, v90, v120
	v_add_f32_e32 v90, v90, v91
	v_add_f32_e32 v91, v67, v121
	v_mul_f32_e64 v120, v68, v68
	v_mul_f32_e64 v121, v69, v69
	v_add_f32_e32 v90, v131, v90
	v_add_f32_e32 v91, v68, v91
	v_add_f32_e32 v120, v120, v90
	v_mul_f32_e32 v90, v69, v69
	v_mov_b32_e32 v121, v69
	v_add_f32_e64 v90, v120, v90
	v_add_f32_e64 v91, v121, v91
	ds_bpermute_b32 v121, v123, v91
	ds_bpermute_b32 v120, v123, v90
	v_and_b32_e32 v131, 0xffff0000, v88
	v_mul_f32_e32 v88, 0xbfb8aa3b, v130
	v_exp_f32_e32 v133, v88
	v_mul_f32_e32 v88, 0xbfb8aa3b, v131
	s_waitcnt lgkmcnt(0)
	v_add_f32_e64 v90, v90, v120
	v_add_f32_e64 v91, v91, v121
	ds_bpermute_b32 v121, v124, v91
	ds_bpermute_b32 v120, v124, v90
	v_exp_f32_e32 v134, v88
	s_waitcnt lgkmcnt(0)
	v_add_f32_e64 v90, v90, v120
	v_add_f32_e64 v91, v91, v121
	s_nop 0
	v_mul_f32_e64 v90, v90, s0
	v_mul_f32_e64 v91, v91, s0
	s_mov_b64 s[0:1], 0x1000
	v_fma_f32 v120, -v91, v91, v90
	v_max_f32_e32 v120, 0, v120
	v_add_f32_e32 v120, 0x358637bd, v120
	v_mul_f32_e32 v121, 0x4b800000, v120
	v_cmp_gt_f32_e32 vcc, s69, v120
	v_add_f32_e64 v110, v110, -v91
	v_add_f32_e64 v111, v111, -v91
	v_lshl_add_u64 v[86:87], v[86:87], 0, s[0:1]
	v_cndmask_b32_e32 v120, v120, v121, vcc
	v_rsq_f32_e32 v129, v120
	v_mov_b32_e32 v120, v142
	v_mov_b32_e32 v121, v143
	v_add_f32_e64 v112, v112, -v91
	v_add_f32_e64 v113, v113, -v91
	v_add_f32_e64 v106, v106, -v91
	v_add_f32_e64 v107, v107, -v91
	v_mul_f32_e32 v132, 0x45800000, v129
	v_cndmask_b32_e32 v88, v129, v132, vcc
	v_add_f32_e32 v129, 1.0, v133
	v_rcp_f32_e32 v132, v129
	v_add_f32_e32 v129, 1.0, v134
	v_rcp_f32_e32 v133, v129
	v_mul_f32_e64 v110, v110, v88
	v_mul_f32_e64 v111, v111, v88
	v_add_f32_e64 v102, v102, -v91
	v_add_f32_e64 v103, v103, -v91
	v_fma_f32 v78, v78, v110, v92
	v_fma_f32 v79, v79, v111, v93
	v_mul_f32_e64 v92, v132, v130
	v_mul_f32_e64 v93, v133, v131
	v_add_f32_e64 v104, v104, -v91
	v_add_f32_e64 v105, v105, -v91
	v_mul_f32_e64 v78, v92, v78
	v_mul_f32_e64 v79, v93, v79
	v_lshlrev_b32_e32 v92, 16, v89
	v_and_b32_e32 v93, 0xffff0000, v89
	v_mul_f32_e32 v89, 0xbfb8aa3b, v92
	v_exp_f32_e32 v89, v89
	v_mul_f32_e32 v110, 0xbfb8aa3b, v93
	v_exp_f32_e32 v111, v110
	v_cvt_pk_bf16_f32 v78, v78, v79
	v_add_f32_e32 v79, 1.0, v89
	v_rcp_f32_e32 v110, v79
	v_add_f32_e32 v79, 1.0, v111
	v_rcp_f32_e32 v111, v79
	v_mul_f32_e64 v112, v112, v88
	v_mul_f32_e64 v113, v113, v88
	v_add_f32_e64 v98, v98, -v91
	v_add_f32_e64 v99, v99, -v91
	v_fma_f32 v80, v80, v112, v94
	v_fma_f32 v81, v81, v113, v95
	v_mul_f32_e64 v92, v110, v92
	v_mul_f32_e64 v93, v111, v93
	v_add_f32_e64 v100, v100, -v91
	v_add_f32_e64 v101, v101, -v91
	v_mul_f32_e64 v80, v92, v80
	v_mul_f32_e64 v81, v93, v81
	v_add_f32_e64 v82, v82, -v91
	v_add_f32_e64 v83, v83, -v91
	v_cvt_pk_bf16_f32 v79, v80, v81
	global_store_dwordx2 v[96:97], v[78:79], off
	s_nop 1
	v_mov_b32_e32 v78, v160
	v_mov_b32_e32 v79, v161
	v_mov_b32_e32 v80, v162
	v_mov_b32_e32 v81, v163
	s_nop 0
	v_mov_b32_e32 v92, v200
	v_mov_b32_e32 v93, v201
	v_mov_b32_e32 v94, v202
	v_mov_b32_e32 v95, v203
	v_add_f32_e64 v84, v84, -v91
	v_add_f32_e64 v85, v85, -v91
	v_add_f32_e64 v74, v74, -v91
	v_add_f32_e64 v75, v75, -v91
	v_add_f32_e64 v76, v76, -v91
	v_add_f32_e64 v77, v77, -v91
	v_add_f32_e64 v70, v70, -v91
	v_add_f32_e64 v71, v71, -v91
	v_add_f32_e64 v72, v72, -v91
	v_add_f32_e64 v73, v73, -v91
	v_add_f32_e64 v66, v66, -v91
	v_add_f32_e64 v67, v67, -v91
	v_add_f32_e64 v68, v68, -v91
	v_add_f32_e64 v69, v69, -v91
	s_mov_b64 s[0:1], 0
	s_and_b64 vcc, exec, s[14:15]
	v_lshlrev_b32_e32 v96, 16, v120
	v_and_b32_e32 v97, 0xffff0000, v120
	v_mul_f32_e32 v89, 0xbfb8aa3b, v96
	v_exp_f32_e32 v89, v89
	v_mul_f32_e32 v110, 0xbfb8aa3b, v97
	v_exp_f32_e32 v113, v110
	v_mov_b32_e32 v110, v144
	v_mov_b32_e32 v111, v145
	v_add_f32_e32 v89, 1.0, v89
	v_rcp_f32_e32 v112, v89
	v_add_f32_e32 v89, 1.0, v113
	v_rcp_f32_e32 v113, v89
	v_mul_f32_e64 v106, v106, v88
	v_mul_f32_e64 v107, v107, v88
	v_fma_f32 v78, v106, v78, v92
	v_fma_f32 v79, v107, v79, v93
	v_mul_f32_e64 v92, v112, v96
	v_mul_f32_e64 v93, v113, v97
	v_add_f32_e64 v106, v108, -v91
	v_add_f32_e64 v107, v109, -v91
	v_mul_f32_e64 v78, v92, v78
	v_mul_f32_e64 v79, v93, v79
	v_lshlrev_b32_e32 v92, 16, v121
	v_and_b32_e32 v93, 0xffff0000, v121
	v_mul_f32_e32 v89, 0xbfb8aa3b, v92
	v_exp_f32_e32 v89, v89
	v_mul_f32_e32 v96, 0xbfb8aa3b, v93
	v_exp_f32_e32 v97, v96
	v_cvt_pk_bf16_f32 v78, v78, v79
	v_add_f32_e32 v79, 1.0, v89
	v_rcp_f32_e32 v96, v79
	v_add_f32_e32 v79, 1.0, v97
	v_rcp_f32_e32 v97, v79
	v_mul_f32_e64 v106, v106, v88
	v_mul_f32_e64 v107, v107, v88
	v_mul_f32_e64 v92, v96, v92
	v_mul_f32_e64 v93, v97, v93
	v_fma_f32 v80, v106, v80, v94
	v_fma_f32 v81, v107, v81, v95
	v_lshlrev_b32_e32 v106, 16, v110
	v_mul_f32_e64 v80, v92, v80
	v_mul_f32_e64 v81, v93, v81
	v_and_b32_e32 v107, 0xffff0000, v110
	v_cvt_pk_bf16_f32 v79, v80, v81
	global_store_dwordx2 v[86:87], v[78:79], off offset:32
	s_nop 1
	v_mov_b32_e32 v78, v164
	v_mov_b32_e32 v79, v165
	v_mov_b32_e32 v80, v166
	v_mov_b32_e32 v81, v167
	s_nop 0
	v_mov_b32_e32 v92, v204
	v_mov_b32_e32 v93, v205
	v_mov_b32_e32 v94, v206
	v_mov_b32_e32 v95, v207
	v_mov_b32_e32 v96, v146
	v_mov_b32_e32 v97, v147
	v_lshlrev_b32_e32 v108, 16, v111
	v_and_b32_e32 v109, 0xffff0000, v111
	v_mul_f32_e32 v89, 0xbfb8aa3b, v106
	v_mul_f32_e32 v110, 0xbfb8aa3b, v107
	v_mul_f32_e32 v111, 0xbfb8aa3b, v108
	v_mul_f32_e32 v112, 0xbfb8aa3b, v109
	v_exp_f32_e32 v89, v89
	v_exp_f32_e32 v110, v110
	v_exp_f32_e32 v111, v111
	v_exp_f32_e32 v112, v112
	v_add_f32_e32 v89, 1.0, v89
	v_add_f32_e32 v113, 1.0, v110
	v_add_f32_e32 v120, 1.0, v111
	v_add_f32_e32 v121, 1.0, v112
	v_rcp_f32_e32 v110, v89
	v_rcp_f32_e32 v111, v113
	v_rcp_f32_e32 v112, v120
	v_rcp_f32_e32 v113, v121
	v_mul_f32_e64 v102, v102, v88
	v_mul_f32_e64 v103, v103, v88
	v_mul_f32_e64 v104, v104, v88
	v_mul_f32_e64 v105, v105, v88
	v_mul_f32_e64 v106, v110, v106
	v_mul_f32_e64 v107, v111, v107
	v_mul_f32_e64 v108, v112, v108
	v_mul_f32_e64 v109, v113, v109
	v_fma_f32 v78, v102, v78, v92
	v_fma_f32 v79, v103, v79, v93
	v_fma_f32 v80, v104, v80, v94
	v_fma_f32 v81, v105, v81, v95
	v_mul_f32_e64 v78, v106, v78
	v_mul_f32_e64 v79, v107, v79
	v_mul_f32_e64 v80, v108, v80
	v_mul_f32_e64 v81, v109, v81
	v_cvt_pk_bf16_f32 v78, v78, v79
	v_cvt_pk_bf16_f32 v79, v80, v81
	global_store_dwordx2 v[86:87], v[78:79], off offset:64
	s_nop 1
	v_mov_b32_e32 v78, v168
	v_mov_b32_e32 v79, v169
	v_mov_b32_e32 v80, v170
	v_mov_b32_e32 v81, v171
	s_nop 0
	v_mov_b32_e32 v92, v208
	v_mov_b32_e32 v93, v209
	v_mov_b32_e32 v94, v210
	v_mov_b32_e32 v95, v211
	v_mov_b32_e32 v102, v148
	v_mov_b32_e32 v103, v149
	v_lshlrev_b32_e32 v104, 16, v96
	v_and_b32_e32 v105, 0xffff0000, v96
	v_lshlrev_b32_e32 v96, 16, v97
	v_and_b32_e32 v97, 0xffff0000, v97
	v_mul_f32_e32 v89, 0xbfb8aa3b, v104
	v_mul_f32_e32 v106, 0xbfb8aa3b, v105
	v_mul_f32_e32 v107, 0xbfb8aa3b, v96
	v_mul_f32_e32 v108, 0xbfb8aa3b, v97
	v_exp_f32_e32 v89, v89
	v_exp_f32_e32 v106, v106
	v_exp_f32_e32 v107, v107
	v_exp_f32_e32 v108, v108
	v_add_f32_e32 v89, 1.0, v89
	v_add_f32_e32 v109, 1.0, v106
	v_add_f32_e32 v110, 1.0, v107
	v_add_f32_e32 v111, 1.0, v108
	v_rcp_f32_e32 v106, v89
	v_rcp_f32_e32 v107, v109
	v_rcp_f32_e32 v108, v110
	v_rcp_f32_e32 v109, v111
	v_mul_f32_e64 v98, v98, v88
	v_mul_f32_e64 v99, v99, v88
	v_mul_f32_e64 v100, v100, v88
	v_mul_f32_e64 v101, v101, v88
	v_mul_f32_e64 v104, v106, v104
	v_mul_f32_e64 v105, v107, v105
	v_mul_f32_e64 v96, v108, v96
	v_mul_f32_e64 v97, v109, v97
	v_fma_f32 v78, v98, v78, v92
	v_fma_f32 v79, v99, v79, v93
	v_fma_f32 v80, v100, v80, v94
	v_fma_f32 v81, v101, v81, v95
	v_mul_f32_e64 v78, v104, v78
	v_mul_f32_e64 v79, v105, v79
	v_mul_f32_e64 v80, v96, v80
	v_mul_f32_e64 v81, v97, v81
	v_cvt_pk_bf16_f32 v78, v78, v79
	v_cvt_pk_bf16_f32 v79, v80, v81
	global_store_dwordx2 v[86:87], v[78:79], off offset:96
	s_nop 1
	v_mov_b32_e32 v78, v172
	v_mov_b32_e32 v79, v173
	v_mov_b32_e32 v80, v174
	v_mov_b32_e32 v81, v175
	s_nop 0
	v_mov_b32_e32 v92, v212
	v_mov_b32_e32 v93, v213
	v_mov_b32_e32 v94, v214
	v_mov_b32_e32 v95, v215
	v_mov_b32_e32 v96, v150
	v_mov_b32_e32 v97, v151
	v_lshlrev_b32_e32 v98, 16, v102
	v_and_b32_e32 v99, 0xffff0000, v102
	v_lshlrev_b32_e32 v100, 16, v103
	v_and_b32_e32 v101, 0xffff0000, v103
	v_mul_f32_e32 v89, 0xbfb8aa3b, v98
	v_mul_f32_e32 v102, 0xbfb8aa3b, v99
	v_mul_f32_e32 v103, 0xbfb8aa3b, v100
	v_mul_f32_e32 v104, 0xbfb8aa3b, v101
	v_exp_f32_e32 v89, v89
	v_exp_f32_e32 v102, v102
	v_exp_f32_e32 v103, v103
	v_exp_f32_e32 v104, v104
	v_add_f32_e32 v89, 1.0, v89
	v_add_f32_e32 v105, 1.0, v102
	v_add_f32_e32 v106, 1.0, v103
	v_add_f32_e32 v107, 1.0, v104
	v_rcp_f32_e32 v102, v89
	v_rcp_f32_e32 v103, v105
	v_rcp_f32_e32 v104, v106
	v_rcp_f32_e32 v105, v107
	v_mul_f32_e64 v82, v82, v88
	v_mul_f32_e64 v83, v83, v88
	v_mul_f32_e64 v84, v84, v88
	v_mul_f32_e64 v85, v85, v88
	v_mul_f32_e64 v98, v102, v98
	v_mul_f32_e64 v99, v103, v99
	v_mul_f32_e64 v100, v104, v100
	v_mul_f32_e64 v101, v105, v101
	v_fma_f32 v78, v82, v78, v92
	v_fma_f32 v79, v83, v79, v93
	v_fma_f32 v80, v84, v80, v94
	v_fma_f32 v81, v85, v81, v95
	v_mul_f32_e64 v78, v98, v78
	v_mul_f32_e64 v79, v99, v79
	v_mul_f32_e64 v80, v100, v80
	v_mul_f32_e64 v81, v101, v81
	v_cvt_pk_bf16_f32 v78, v78, v79
	v_cvt_pk_bf16_f32 v79, v80, v81
	global_store_dwordx2 v[86:87], v[78:79], off offset:128
	s_nop 1
	v_mov_b32_e32 v78, v176
	v_mov_b32_e32 v79, v177
	v_mov_b32_e32 v80, v178
	v_mov_b32_e32 v81, v179
	s_nop 0
	v_mov_b32_e32 v92, v216
	v_mov_b32_e32 v93, v217
	v_mov_b32_e32 v94, v218
	v_mov_b32_e32 v95, v219
	v_mov_b32_e32 v82, v152
	v_mov_b32_e32 v83, v153
	v_lshlrev_b32_e32 v84, 16, v96
	v_and_b32_e32 v85, 0xffff0000, v96
	v_lshlrev_b32_e32 v96, 16, v97
	v_and_b32_e32 v97, 0xffff0000, v97
	v_mul_f32_e32 v89, 0xbfb8aa3b, v84
	v_mul_f32_e32 v98, 0xbfb8aa3b, v85
	v_mul_f32_e32 v99, 0xbfb8aa3b, v96
	v_mul_f32_e32 v100, 0xbfb8aa3b, v97
	v_exp_f32_e32 v89, v89
	v_exp_f32_e32 v98, v98
	v_exp_f32_e32 v99, v99
	v_exp_f32_e32 v100, v100
	v_add_f32_e32 v89, 1.0, v89
	v_add_f32_e32 v101, 1.0, v98
	v_add_f32_e32 v102, 1.0, v99
	v_add_f32_e32 v103, 1.0, v100
	v_rcp_f32_e32 v98, v89
	v_rcp_f32_e32 v99, v101
	v_rcp_f32_e32 v100, v102
	v_rcp_f32_e32 v101, v103
	v_mul_f32_e64 v74, v74, v88
	v_mul_f32_e64 v75, v75, v88
	v_mul_f32_e64 v76, v76, v88
	v_mul_f32_e64 v77, v77, v88
	v_mul_f32_e64 v84, v98, v84
	v_mul_f32_e64 v85, v99, v85
	v_mul_f32_e64 v96, v100, v96
	v_mul_f32_e64 v97, v101, v97
	v_fma_f32 v74, v74, v78, v92
	v_fma_f32 v75, v75, v79, v93
	v_fma_f32 v76, v76, v80, v94
	v_fma_f32 v77, v77, v81, v95
	v_mul_f32_e64 v74, v84, v74
	v_mul_f32_e64 v75, v85, v75
	v_mul_f32_e64 v76, v96, v76
	v_mul_f32_e64 v77, v97, v77
	v_cvt_pk_bf16_f32 v74, v74, v75
	v_cvt_pk_bf16_f32 v75, v76, v77
	global_store_dwordx2 v[86:87], v[74:75], off offset:160
	s_nop 1
	v_mov_b32_e32 v74, v180
	v_mov_b32_e32 v75, v181
	v_mov_b32_e32 v76, v182
	v_mov_b32_e32 v77, v183
	s_nop 0
	v_mov_b32_e32 v78, v220
	v_mov_b32_e32 v79, v221
	v_mov_b32_e32 v80, v222
	v_mov_b32_e32 v81, v223
	v_mov_b32_e32 v84, v154
	v_mov_b32_e32 v85, v155
	v_lshlrev_b32_e32 v92, 16, v82
	v_and_b32_e32 v93, 0xffff0000, v82
	v_lshlrev_b32_e32 v82, 16, v83
	v_and_b32_e32 v83, 0xffff0000, v83
	v_mul_f32_e32 v89, 0xbfb8aa3b, v92
	v_mul_f32_e32 v94, 0xbfb8aa3b, v93
	v_mul_f32_e32 v95, 0xbfb8aa3b, v82
	v_mul_f32_e32 v96, 0xbfb8aa3b, v83
	v_exp_f32_e32 v89, v89
	v_exp_f32_e32 v94, v94
	v_exp_f32_e32 v95, v95
	v_exp_f32_e32 v96, v96
	v_add_f32_e32 v89, 1.0, v89
	v_add_f32_e32 v97, 1.0, v94
	v_add_f32_e32 v98, 1.0, v95
	v_add_f32_e32 v99, 1.0, v96
	v_rcp_f32_e32 v94, v89
	v_rcp_f32_e32 v95, v97
	v_rcp_f32_e32 v96, v98
	v_rcp_f32_e32 v97, v99
	v_mul_f32_e64 v70, v70, v88
	v_mul_f32_e64 v71, v71, v88
	v_mul_f32_e64 v72, v72, v88
	v_mul_f32_e64 v73, v73, v88
	v_mul_f32_e64 v92, v94, v92
	v_mul_f32_e64 v93, v95, v93
	v_mul_f32_e64 v82, v96, v82
	v_mul_f32_e64 v83, v97, v83
	v_mul_f32_e64 v66, v66, v88
	v_mul_f32_e64 v67, v67, v88
	v_mul_f32_e64 v68, v68, v88
	v_mul_f32_e64 v69, v69, v88
	v_fma_f32 v70, v70, v74, v78
	v_fma_f32 v71, v71, v75, v79
	v_fma_f32 v72, v72, v76, v80
	v_fma_f32 v73, v73, v77, v81
	v_mul_f32_e64 v70, v92, v70
	v_mul_f32_e64 v71, v93, v71
	v_mul_f32_e64 v72, v82, v72
	v_mul_f32_e64 v73, v83, v73
	v_cvt_pk_bf16_f32 v70, v70, v71
	v_cvt_pk_bf16_f32 v71, v72, v73
	global_store_dwordx2 v[86:87], v[70:71], off offset:192
	s_nop 1
	v_mov_b32_e32 v70, v184
	v_mov_b32_e32 v71, v185
	v_mov_b32_e32 v72, v186
	v_mov_b32_e32 v73, v187
	s_nop 0
	v_mov_b32_e32 v74, v224
	v_mov_b32_e32 v75, v225
	v_mov_b32_e32 v76, v226
	v_mov_b32_e32 v77, v227
	v_lshlrev_b32_e32 v78, 16, v84
	v_and_b32_e32 v79, 0xffff0000, v84
	v_lshlrev_b32_e32 v80, 16, v85
	v_and_b32_e32 v81, 0xffff0000, v85
	v_mul_f32_e32 v82, 0xbfb8aa3b, v78
	v_mul_f32_e32 v83, 0xbfb8aa3b, v79
	v_mul_f32_e32 v84, 0xbfb8aa3b, v80
	v_mul_f32_e32 v85, 0xbfb8aa3b, v81
	v_exp_f32_e32 v82, v82
	v_exp_f32_e32 v83, v83
	v_exp_f32_e32 v84, v84
	v_exp_f32_e32 v85, v85
	v_add_f32_e32 v82, 1.0, v82
	v_add_f32_e32 v83, 1.0, v83
	v_add_f32_e32 v84, 1.0, v84
	v_add_f32_e32 v85, 1.0, v85
	v_rcp_f32_e32 v82, v82
	v_rcp_f32_e32 v83, v83
	v_rcp_f32_e32 v84, v84
	v_rcp_f32_e32 v85, v85
	v_mul_f32_e64 v78, v82, v78
	v_mul_f32_e64 v79, v83, v79
	v_mul_f32_e64 v80, v84, v80
	v_mul_f32_e64 v81, v85, v81
	v_fma_f32 v66, v66, v70, v74
	v_fma_f32 v67, v67, v71, v75
	v_fma_f32 v68, v68, v72, v76
	v_fma_f32 v69, v69, v73, v77
	v_mul_f32_e64 v66, v78, v66
	v_mul_f32_e64 v67, v79, v67
	v_mul_f32_e64 v68, v80, v68
	v_mul_f32_e64 v69, v81, v69
	v_cvt_pk_bf16_f32 v66, v66, v67
	v_cvt_pk_bf16_f32 v67, v68, v69
	global_store_dwordx2 v[86:87], v[66:67], off offset:224
	s_cbranch_vccz .LBB0_1084
	s_add_i32 s6, s6, s82
	s_cmpk_gt_i32 s6, 0x1ff
	s_barrier
	s_cbranch_scc0 .LBB0_1083
